# compress unit: 16 dependent pe.w1 partial-sum loads issued together (counted vmcnt)
# baseline (speedup 1.0000x reference)
.LBB0_884:
	v_add_u32_e32 v0, 0x400, v162
	s_nop 5
	ds_write2_b32 v0, v52, v53 offset0:2 offset1:131
	v_lshlrev_b32_e32 v0, 2, v147
	v_lshl_or_b32 v0, s44, 13, v0
	v_lshl_add_u64 v[4:5], s[38:39], 0, v[0:1]
	v_add_co_u32_e32 v2, vcc, 0x5c0000, v4
	s_mov_b64 s[40:41], 0x5c0000
	s_nop 0
	v_addc_co_u32_e32 v3, vcc, 0, v5, vcc
	ds_write2_b32 v162, v50, v51 offset1:129
	s_waitcnt lgkmcnt(0)
	s_barrier
	v_lshl_add_u64 v[6:7], v[4:5], 0, s[40:41]
	global_load_dword v0, v[2:3], off
	s_mov_b32 s41, 0x5c1000
	global_load_dword v3, v[6:7], off offset:512
	v_add_co_u32_e32 v4, vcc, s41, v4
	v_mov_b32_e32 v2, 0
	s_nop 0
	v_addc_co_u32_e32 v5, vcc, 0, v5, vcc
	s_mov_b32 s40, 0
	global_load_dword v8, v[6:7], off offset:1024
	global_load_dword v9, v[6:7], off offset:1536
	global_load_dword v10, v[6:7], off offset:2048
	global_load_dword v11, v[6:7], off offset:2560
	global_load_dword v12, v[6:7], off offset:3072
	global_load_dword v13, v[6:7], off offset:3584
	global_load_dword v14, v[4:5], off
	global_load_dword v15, v[4:5], off offset:512
	global_load_dword v16, v[4:5], off offset:1024
	global_load_dword v17, v[4:5], off offset:1536
	global_load_dword v18, v[4:5], off offset:2048
	global_load_dword v19, v[4:5], off offset:2560
	global_load_dword v20, v[4:5], off offset:3072
	global_load_dword v21, v[4:5], off offset:3584
	s_waitcnt vmcnt(15)
	v_add_f32_e32 v0, 0, v0
	s_waitcnt vmcnt(14)
	v_add_f32_e32 v0, v0, v3
	s_waitcnt vmcnt(13)
	v_add_f32_e32 v0, v0, v8
	s_waitcnt vmcnt(12)
	v_add_f32_e32 v0, v0, v9
	s_waitcnt vmcnt(11)
	v_add_f32_e32 v0, v0, v10
	s_waitcnt vmcnt(10)
	v_add_f32_e32 v0, v0, v11
	s_waitcnt vmcnt(9)
	v_add_f32_e32 v0, v0, v12
	s_waitcnt vmcnt(8)
	v_add_f32_e32 v0, v0, v13
	s_waitcnt vmcnt(7)
	v_add_f32_e32 v0, v0, v14
	s_waitcnt vmcnt(6)
	v_add_f32_e32 v0, v0, v15
	s_waitcnt vmcnt(5)
	v_add_f32_e32 v0, v0, v16
	s_waitcnt vmcnt(4)
	v_add_f32_e32 v0, v0, v17
	s_waitcnt vmcnt(3)
	v_add_f32_e32 v0, v0, v18
	s_waitcnt vmcnt(2)
	v_add_f32_e32 v0, v0, v19
	s_waitcnt vmcnt(1)
	v_add_f32_e32 v0, v0, v20
	s_waitcnt vmcnt(0)
	v_add_f32_e32 v0, v0, v21
	ds_read_b32 v3, v163
	s_waitcnt lgkmcnt(0)
	v_add_f32_e32 v3, v0, v3
	v_mul_f32_e32 v4, 0xbfb8aa3b, v3
	v_exp_f32_e32 v4, v4
	s_nop 0
	v_add_f32_e32 v4, 1.0, v4
	v_rcp_f32_e32 v4, v4
	s_nop 0
	v_mul_f32_e32 v3, v3, v4
	ds_write_b32 v163, v3
	ds_read_b32 v3, v163 offset:2064
	s_waitcnt lgkmcnt(0)
	v_add_f32_e32 v3, v0, v3
	v_mul_f32_e32 v4, 0xbfb8aa3b, v3
	v_exp_f32_e32 v4, v4
	s_nop 0
	v_add_f32_e32 v4, 1.0, v4
	v_rcp_f32_e32 v4, v4
	s_nop 0
	v_mul_f32_e32 v3, v3, v4
	ds_write_b32 v163, v3 offset:2064
	ds_read_b32 v3, v163 offset:4128
	s_waitcnt lgkmcnt(0)
	v_add_f32_e32 v3, v0, v3
	v_mul_f32_e32 v4, 0xbfb8aa3b, v3
	v_exp_f32_e32 v4, v4
	s_nop 0
	v_add_f32_e32 v4, 1.0, v4
	v_rcp_f32_e32 v4, v4
	s_nop 0
	v_mul_f32_e32 v3, v3, v4
	ds_write_b32 v163, v3 offset:4128
	ds_read_b32 v3, v163 offset:6192
	s_waitcnt lgkmcnt(0)
	v_add_f32_e32 v0, v0, v3
	v_mul_f32_e32 v3, 0xbfb8aa3b, v0
	v_exp_f32_e32 v3, v3
	s_nop 0
	v_add_f32_e32 v3, 1.0, v3
	v_rcp_f32_e32 v3, v3
	s_nop 0
	v_mul_f32_e32 v0, v0, v3
	ds_write_b32 v163, v0 offset:6192
	v_mov_b32_e32 v0, v159
	v_mov_b32_e32 v3, v2
	s_waitcnt lgkmcnt(0)
	s_barrier

.LBB0_2071:
	v_add_u32_e32 v0, 0x400, v163
	s_nop 5
	ds_write2_b32 v0, v52, v53 offset0:2 offset1:131
	v_lshlrev_b32_e32 v0, 2, v147
	v_lshl_or_b32 v0, s46, 13, v0
	v_lshl_add_u64 v[4:5], s[38:39], 0, v[0:1]
	v_add_co_u32_e32 v2, vcc, 0x5c0000, v4
	s_mov_b64 s[40:41], 0x5c0000
	s_nop 0
	v_addc_co_u32_e32 v3, vcc, 0, v5, vcc
	ds_write2_b32 v163, v50, v51 offset1:129
	s_waitcnt lgkmcnt(0)
	s_barrier
	v_lshl_add_u64 v[6:7], v[4:5], 0, s[40:41]
	global_load_dword v0, v[2:3], off
	s_mov_b32 s41, 0x5c1000
	global_load_dword v3, v[6:7], off offset:512
	v_add_co_u32_e32 v4, vcc, s41, v4
	v_mov_b32_e32 v2, 0
	s_nop 0
	v_addc_co_u32_e32 v5, vcc, 0, v5, vcc
	s_mov_b32 s40, 0
	global_load_dword v8, v[6:7], off offset:1024
	global_load_dword v9, v[6:7], off offset:1536
	global_load_dword v10, v[6:7], off offset:2048
	global_load_dword v11, v[6:7], off offset:2560
	global_load_dword v12, v[6:7], off offset:3072
	global_load_dword v13, v[6:7], off offset:3584
	global_load_dword v14, v[4:5], off
	global_load_dword v15, v[4:5], off offset:512
	global_load_dword v16, v[4:5], off offset:1024
	global_load_dword v17, v[4:5], off offset:1536
	global_load_dword v18, v[4:5], off offset:2048
	global_load_dword v19, v[4:5], off offset:2560
	global_load_dword v20, v[4:5], off offset:3072
	global_load_dword v21, v[4:5], off offset:3584
	s_waitcnt vmcnt(15)
	v_add_f32_e32 v0, 0, v0
	s_waitcnt vmcnt(14)
	v_add_f32_e32 v0, v0, v3
	s_waitcnt vmcnt(13)
	v_add_f32_e32 v0, v0, v8
	s_waitcnt vmcnt(12)
	v_add_f32_e32 v0, v0, v9
	s_waitcnt vmcnt(11)
	v_add_f32_e32 v0, v0, v10
	s_waitcnt vmcnt(10)
	v_add_f32_e32 v0, v0, v11
	s_waitcnt vmcnt(9)
	v_add_f32_e32 v0, v0, v12
	s_waitcnt vmcnt(8)
	v_add_f32_e32 v0, v0, v13
	s_waitcnt vmcnt(7)
	v_add_f32_e32 v0, v0, v14
	s_waitcnt vmcnt(6)
	v_add_f32_e32 v0, v0, v15
	s_waitcnt vmcnt(5)
	v_add_f32_e32 v0, v0, v16
	s_waitcnt vmcnt(4)
	v_add_f32_e32 v0, v0, v17
	s_waitcnt vmcnt(3)
	v_add_f32_e32 v0, v0, v18
	s_waitcnt vmcnt(2)
	v_add_f32_e32 v0, v0, v19
	s_waitcnt vmcnt(1)
	v_add_f32_e32 v0, v0, v20
	s_waitcnt vmcnt(0)
	v_add_f32_e32 v0, v0, v21
	ds_read_b32 v3, v164
	s_waitcnt lgkmcnt(0)
	v_add_f32_e32 v3, v0, v3
	v_mul_f32_e32 v4, 0xbfb8aa3b, v3
	v_exp_f32_e32 v4, v4
	s_nop 0
	v_add_f32_e32 v4, 1.0, v4
	v_rcp_f32_e32 v4, v4
	s_nop 0
	v_mul_f32_e32 v3, v3, v4
	ds_write_b32 v164, v3
	ds_read_b32 v3, v164 offset:2064
	s_waitcnt lgkmcnt(0)
	v_add_f32_e32 v3, v0, v3
	v_mul_f32_e32 v4, 0xbfb8aa3b, v3
	v_exp_f32_e32 v4, v4
	s_nop 0
	v_add_f32_e32 v4, 1.0, v4
	v_rcp_f32_e32 v4, v4
	s_nop 0
	v_mul_f32_e32 v3, v3, v4
	ds_write_b32 v164, v3 offset:2064
	ds_read_b32 v3, v164 offset:4128
	s_waitcnt lgkmcnt(0)
	v_add_f32_e32 v3, v0, v3
	v_mul_f32_e32 v4, 0xbfb8aa3b, v3
	v_exp_f32_e32 v4, v4
	s_nop 0
	v_add_f32_e32 v4, 1.0, v4
	v_rcp_f32_e32 v4, v4
	s_nop 0
	v_mul_f32_e32 v3, v3, v4
	ds_write_b32 v164, v3 offset:4128
	ds_read_b32 v3, v164 offset:6192
	s_waitcnt lgkmcnt(0)
	v_add_f32_e32 v0, v0, v3
	v_mul_f32_e32 v3, 0xbfb8aa3b, v0
	v_exp_f32_e32 v3, v3
	s_nop 0
	v_add_f32_e32 v3, 1.0, v3
	v_rcp_f32_e32 v3, v3
	s_nop 0
	v_mul_f32_e32 v0, v0, v3
	ds_write_b32 v164, v0 offset:6192
	v_mov_b32_e32 v0, v160
	v_mov_b32_e32 v3, v2
	s_waitcnt lgkmcnt(0)
	s_barrier
